# v93 stack + conv LayerNorm block: hipcc's SLP packing undone (48 v_pk_add/mul/fma fed by v_mov copies -> plain scalar pairs, 128 copies removed)
# speedup vs baseline: 1.0056x; 1.0007x over previous
; #define LAS __attribute__((address_space(3)))
; __global__ void __launch_bounds__(NWAVES * 64, 2) mk_fwd(Args args) {
;     ...
;                 __syncthreads();
;                 {
;                     f32x4 a[8], c[8]; float sm[8];
; #pragma unroll
;                     for (int k = 0; k < 8; ++k) { const int tok = wave * 8 + k; a[k] = *(const LAS f32x4*)(yt + tok * 512 + 4 * lane); c[k] = *(const LAS f32x4*)(yt + tok * 512 + 256 + 4 * lane);
;                         sm[k] = ((a[k][0] + a[k][1]) + (a[k][2] + a[k][3])) + ((c[k][0] + c[k][1]) + (c[k][2] + c[k][3])); }
; #pragma unroll
;                     for (int o = 1; o < 64; o <<= 1) {
; #pragma unroll
;                         for (int k = 0; k < 8; ++k) sm[k] += __shfl_xor(sm[k], o); }
.LBB0_354:
	s_barrier
	ds_read_b128 v[76:79], v168
	ds_read_b128 v[72:75], v168 offset:1024
	ds_read_b128 v[68:71], v168 offset:2048
	ds_read_b128 v[64:67], v168 offset:3072
	ds_read_b128 v[60:63], v168 offset:4096
	ds_read_b128 v[56:59], v168 offset:5120
	ds_read_b128 v[52:55], v168 offset:6144
	ds_read_b128 v[48:51], v168 offset:7168
	s_waitcnt lgkmcnt(7)
	s_waitcnt lgkmcnt(6)
	v_add_f32_e32 v16, v76, v77
	v_add_f32_e32 v17, v72, v73
	v_add_f32_e32 v18, v78, v79
	v_add_f32_e32 v19, v74, v75
	s_waitcnt lgkmcnt(5)
	v_pk_add_f32 v[16:17], v[16:17], v[18:19]
	v_add_f32_e32 v81, v16, v17
	s_waitcnt lgkmcnt(4)
	v_add_f32_e32 v16, v68, v69
	v_add_f32_e32 v17, v64, v65
	v_add_f32_e32 v18, v70, v71
	v_add_f32_e32 v19, v66, v67
	s_waitcnt lgkmcnt(3)
	v_pk_add_f32 v[16:17], v[16:17], v[18:19]
	v_add_f32_e32 v158, v16, v17
	s_waitcnt lgkmcnt(2)
	v_add_f32_e32 v16, v60, v61
	v_add_f32_e32 v17, v56, v57
	v_add_f32_e32 v18, v62, v63
	v_add_f32_e32 v19, v58, v59
	ds_read_b128 v[44:47], v168 offset:8192
	ds_read_b128 v[40:43], v168 offset:9216
	v_pk_add_f32 v[16:17], v[16:17], v[18:19]
	s_waitcnt lgkmcnt(3)
	v_add_f32_e32 v159, v16, v17
	s_waitcnt lgkmcnt(2)
	v_add_f32_e32 v16, v52, v53
	v_add_f32_e32 v17, v48, v49
	v_add_f32_e32 v18, v54, v55
	v_add_f32_e32 v19, v50, v51
	ds_read_b128 v[36:39], v168 offset:10240
	ds_read_b128 v[32:35], v168 offset:11264
	v_pk_add_f32 v[16:17], v[16:17], v[18:19]
	s_waitcnt lgkmcnt(3)
	v_add_f32_e32 v160, v16, v17
	s_waitcnt lgkmcnt(2)
	v_add_f32_e32 v16, v44, v45
	v_add_f32_e32 v17, v40, v41
	v_add_f32_e32 v18, v46, v47
	v_add_f32_e32 v19, v42, v43
	ds_read_b128 v[28:31], v168 offset:12288
	ds_read_b128 v[24:27], v168 offset:13312
	v_pk_add_f32 v[16:17], v[16:17], v[18:19]
	s_waitcnt lgkmcnt(3)
	v_add_f32_e32 v161, v16, v17
	s_waitcnt lgkmcnt(2)
	v_add_f32_e32 v16, v36, v37
	v_add_f32_e32 v17, v32, v33
	v_add_f32_e32 v18, v38, v39
	v_add_f32_e32 v19, v34, v35
	s_waitcnt lgkmcnt(1)
	v_pk_add_f32 v[16:17], v[16:17], v[18:19]
	v_add_f32_e32 v162, v16, v17
	s_waitcnt lgkmcnt(0)
	v_add_f32_e32 v152, v28, v29
	v_add_f32_e32 v153, v24, v25
	ds_read_b128 v[20:23], v168 offset:14336
	ds_read_b128 v[16:19], v168 offset:15360
	v_add_f32_e32 v154, v30, v31
	v_add_f32_e32 v155, v26, v27
	s_waitcnt lgkmcnt(1)
	v_pk_add_f32 v[152:153], v[152:153], v[154:155]
	v_add_f32_e32 v163, v152, v153
	s_waitcnt lgkmcnt(0)
	v_add_f32_e32 v152, v20, v21
	v_add_f32_e32 v153, v16, v17
	v_add_f32_e32 v154, v22, v23
	v_add_f32_e32 v155, v18, v19
	v_pk_add_f32 v[152:153], v[152:153], v[154:155]
	v_add_f32_e32 v152, v152, v153
	s_waitcnt lgkmcnt(3)
	v_add_f32_dpp v81, v81, v81 quad_perm:[1,0,3,2] row_mask:0xf bank_mask:0xf
	s_waitcnt lgkmcnt(2)
	v_add_f32_dpp v154, v159, v159 quad_perm:[1,0,3,2] row_mask:0xf bank_mask:0xf
	s_waitcnt lgkmcnt(3)
	v_add_f32_dpp v153, v158, v158 quad_perm:[1,0,3,2] row_mask:0xf bank_mask:0xf
	s_waitcnt lgkmcnt(4)
	v_add_f32_dpp v155, v160, v160 quad_perm:[1,0,3,2] row_mask:0xf bank_mask:0xf
	s_waitcnt lgkmcnt(3)
	v_add_f32_dpp v156, v161, v161 quad_perm:[1,0,3,2] row_mask:0xf bank_mask:0xf
	s_waitcnt lgkmcnt(2)
	v_add_f32_dpp v152, v152, v152 quad_perm:[1,0,3,2] row_mask:0xf bank_mask:0xf
	s_waitcnt lgkmcnt(3)
	v_add_f32_dpp v157, v162, v162 quad_perm:[1,0,3,2] row_mask:0xf bank_mask:0xf
	s_waitcnt lgkmcnt(2)
	v_add_f32_dpp v158, v163, v163 quad_perm:[1,0,3,2] row_mask:0xf bank_mask:0xf
	s_waitcnt lgkmcnt(4)
	v_add_f32_dpp v81, v81, v81 quad_perm:[2,3,0,1] row_mask:0xf bank_mask:0xf
	s_waitcnt lgkmcnt(3)
	v_add_f32_dpp v153, v153, v153 quad_perm:[2,3,0,1] row_mask:0xf bank_mask:0xf
	s_waitcnt lgkmcnt(4)
	v_add_f32_dpp v155, v155, v155 quad_perm:[2,3,0,1] row_mask:0xf bank_mask:0xf
	s_waitcnt lgkmcnt(3)
	v_add_f32_dpp v156, v156, v156 quad_perm:[2,3,0,1] row_mask:0xf bank_mask:0xf
	s_waitcnt lgkmcnt(4)
	v_add_f32_dpp v154, v154, v154 quad_perm:[2,3,0,1] row_mask:0xf bank_mask:0xf
	s_waitcnt lgkmcnt(4)
	v_add_f32_dpp v157, v157, v157 quad_perm:[2,3,0,1] row_mask:0xf bank_mask:0xf
	s_waitcnt lgkmcnt(3)
	v_add_f32_dpp v158, v158, v158 quad_perm:[2,3,0,1] row_mask:0xf bank_mask:0xf
	s_waitcnt lgkmcnt(4)
	v_add_f32_dpp v81, v81, v81 row_half_mirror row_mask:0xf bank_mask:0xf
	s_waitcnt lgkmcnt(3)
	v_add_f32_dpp v153, v153, v153 row_half_mirror row_mask:0xf bank_mask:0xf
	s_waitcnt lgkmcnt(4)
	v_add_f32_dpp v152, v152, v152 quad_perm:[2,3,0,1] row_mask:0xf bank_mask:0xf
	s_waitcnt lgkmcnt(4)
	v_add_f32_dpp v154, v154, v154 row_half_mirror row_mask:0xf bank_mask:0xf
	s_waitcnt lgkmcnt(3)
	v_add_f32_dpp v155, v155, v155 row_half_mirror row_mask:0xf bank_mask:0xf
	s_waitcnt lgkmcnt(4)
	v_add_f32_dpp v157, v157, v157 row_half_mirror row_mask:0xf bank_mask:0xf
	s_waitcnt lgkmcnt(3)
	v_add_f32_dpp v158, v158, v158 row_half_mirror row_mask:0xf bank_mask:0xf
	s_waitcnt lgkmcnt(4)
	v_add_f32_dpp v156, v156, v156 row_half_mirror row_mask:0xf bank_mask:0xf
	s_waitcnt lgkmcnt(4)
	v_add_f32_dpp v152, v152, v152 row_half_mirror row_mask:0xf bank_mask:0xf
	s_waitcnt lgkmcnt(3)
	v_add_f32_dpp v81, v81, v81 row_mirror row_mask:0xf bank_mask:0xf
	s_waitcnt lgkmcnt(4)
	v_add_f32_dpp v154, v154, v154 row_mirror row_mask:0xf bank_mask:0xf
	s_waitcnt lgkmcnt(3)
	v_add_f32_dpp v155, v155, v155 row_mirror row_mask:0xf bank_mask:0xf
	v_mov_b32_e32 v163, v81
	s_nop 1
	v_permlane16_swap_b32_e32 v81, v163
	s_waitcnt lgkmcnt(4)
	v_add_f32_dpp v153, v153, v153 row_mirror row_mask:0xf bank_mask:0xf
	s_waitcnt lgkmcnt(4)
	v_add_f32_dpp v156, v156, v156 row_mirror row_mask:0xf bank_mask:0xf
	s_waitcnt lgkmcnt(3)
	v_add_f32_dpp v157, v157, v157 row_mirror row_mask:0xf bank_mask:0xf
	v_mov_b32_e32 v159, v153
	s_nop 1
	v_permlane16_swap_b32_e32 v153, v159
	v_mov_b32_e32 v160, v154
	s_nop 1
	v_permlane16_swap_b32_e32 v154, v160
	s_waitcnt lgkmcnt(4)
; __global__ void __launch_bounds__(NWAVES * 64, 2) mk_fwd(Args args) {
;     ...
; #pragma unroll
;                     for (int k = 0; k < 8; ++k) { const float mu = sm[k] * (1.f / 512.f); a[k] = a[k] - mu; c[k] = c[k] - mu;
;                         sm[k] = ((a[k][0] * a[k][0] + a[k][1] * a[k][1]) + (a[k][2] * a[k][2] + a[k][3] * a[k][3])) + ((c[k][0] * c[k][0] + c[k][1] * c[k][1]) + (c[k][2] * c[k][2] + c[k][3] * c[k][3])); }
; #pragma unroll
;                     for (int o = 1; o < 64; o <<= 1) {
; #pragma unroll
;                         for (int k = 0; k < 8; ++k) sm[k] += __shfl_xor(sm[k], o); }
	v_add_f32_dpp v152, v152, v152 row_mirror row_mask:0xf bank_mask:0xf
	s_waitcnt lgkmcnt(3)
	v_add_f32_e32 v81, v81, v163
	v_mov_b32_e32 v162, v156
	s_nop 1
	v_permlane16_swap_b32_e32 v156, v162
	v_mov_b32_e32 v163, v157
	s_nop 1
	v_permlane16_swap_b32_e32 v157, v163
	s_waitcnt lgkmcnt(4)
	v_add_f32_dpp v158, v158, v158 row_mirror row_mask:0xf bank_mask:0xf
	v_mov_b32_e32 v161, v155
	s_nop 1
	v_permlane16_swap_b32_e32 v155, v161
	s_waitcnt lgkmcnt(4)
	v_add_f32_e32 v153, v153, v159
	s_waitcnt lgkmcnt(3)
	v_add_f32_e32 v154, v154, v160
	s_waitcnt lgkmcnt(2)
	v_add_f32_e32 v156, v156, v162
	s_waitcnt lgkmcnt(1)
	v_add_f32_e32 v157, v157, v163
	v_mov_b32_e32 v159, v158
	s_nop 1
	v_permlane16_swap_b32_e32 v158, v159
	v_mov_b32_e32 v160, v152
	s_nop 1
	v_permlane16_swap_b32_e32 v152, v160
	v_mov_b32_e32 v162, v153
	s_nop 1
	v_permlane32_swap_b32_e32 v153, v162
	v_mov_b32_e32 v163, v154
	s_nop 1
	v_permlane32_swap_b32_e32 v154, v163
	s_waitcnt lgkmcnt(4)
	v_add_f32_e32 v155, v155, v161
	v_mov_b32_e32 v161, v81
	s_nop 1
	v_permlane32_swap_b32_e32 v81, v161
	s_waitcnt lgkmcnt(4)
	v_add_f32_e32 v158, v158, v159
	s_waitcnt lgkmcnt(3)
	v_add_f32_e32 v152, v152, v160
	s_waitcnt lgkmcnt(2)
	v_add_f32_e32 v159, v153, v162
	s_waitcnt lgkmcnt(1)
	v_add_f32_e32 v160, v154, v163
	v_mov_b32_e32 v153, v155
	s_nop 1
	v_permlane32_swap_b32_e32 v155, v153
	v_mov_b32_e32 v154, v156
	s_nop 1
	v_permlane32_swap_b32_e32 v156, v154
	s_waitcnt lgkmcnt(2)
	v_add_f32_e32 v81, v81, v161
	v_mov_b32_e32 v161, v157
	s_nop 1
	v_permlane32_swap_b32_e32 v157, v161
	v_mov_b32_e32 v162, v158
	s_nop 1
	v_permlane32_swap_b32_e32 v158, v162
	v_mov_b32_e32 v163, v152
	s_nop 1
	v_permlane32_swap_b32_e32 v152, v163
	v_fmamk_f32 v77, v81, 0xbb000000, v77
	v_fmamk_f32 v73, v81, 0xbb000000, v73
	s_waitcnt lgkmcnt(4)
	v_add_f32_e32 v164, v155, v153
	s_waitcnt lgkmcnt(3)
	v_add_f32_e32 v165, v156, v154
	v_fmamk_f32 v79, v81, 0xbb000000, v79
	v_fmac_f32_e32 v76, 0xbb000000, v81
	v_fmamk_f32 v75, v81, 0xbb000000, v75
	v_fmac_f32_e32 v72, 0xbb000000, v81
	s_waitcnt lgkmcnt(2)
	v_add_f32_e32 v161, v157, v161
	s_waitcnt lgkmcnt(1)
	v_add_f32_e32 v158, v158, v162
	s_waitcnt lgkmcnt(0)
	v_add_f32_e32 v162, v152, v163
	v_fmamk_f32 v78, v81, 0xbb000000, v78
	v_fmamk_f32 v74, v81, 0xbb000000, v74
	v_mul_f32_e32 v154, v77, v77
	v_mul_f32_e32 v155, v73, v73
	v_fma_f32 v152, v76, v76, v154
	v_fma_f32 v153, v72, v72, v155
	v_mul_f32_e32 v156, v79, v79
	v_mul_f32_e32 v157, v75, v75
	v_fmamk_f32 v69, v159, 0xbb000000, v69
	v_fma_f32 v154, v78, v78, v156
	v_fma_f32 v155, v74, v74, v157
	v_fmamk_f32 v65, v159, 0xbb000000, v65
	v_pk_add_f32 v[152:153], v[152:153], v[154:155]
	v_fmamk_f32 v71, v159, 0xbb000000, v71
	v_fmac_f32_e32 v68, 0xbb000000, v159
	v_fmamk_f32 v67, v159, 0xbb000000, v67
	v_fmac_f32_e32 v64, 0xbb000000, v159
	v_add_f32_e32 v81, v152, v153
	v_fmamk_f32 v70, v159, 0xbb000000, v70
	v_fmamk_f32 v66, v159, 0xbb000000, v66
	v_mul_f32_e32 v154, v69, v69
	v_mul_f32_e32 v155, v65, v65
	v_fma_f32 v152, v68, v68, v154
	v_fma_f32 v153, v64, v64, v155
	v_mul_f32_e32 v156, v71, v71
	v_mul_f32_e32 v157, v67, v67
	v_fmamk_f32 v61, v160, 0xbb000000, v61
	v_fma_f32 v154, v70, v70, v156
	v_fma_f32 v155, v66, v66, v157
	v_fmamk_f32 v57, v160, 0xbb000000, v57
	v_pk_add_f32 v[152:153], v[152:153], v[154:155]
	v_fmamk_f32 v63, v160, 0xbb000000, v63
	v_fmac_f32_e32 v60, 0xbb000000, v160
	v_fmamk_f32 v59, v160, 0xbb000000, v59
	v_fmac_f32_e32 v56, 0xbb000000, v160
	v_add_f32_e32 v159, v152, v153
	v_fmamk_f32 v62, v160, 0xbb000000, v62
	v_fmamk_f32 v58, v160, 0xbb000000, v58
	v_mul_f32_e32 v154, v61, v61
	v_mul_f32_e32 v155, v57, v57
	v_fma_f32 v152, v60, v60, v154
	v_fma_f32 v153, v56, v56, v155
	v_mul_f32_e32 v156, v63, v63
	v_mul_f32_e32 v157, v59, v59
	v_fmamk_f32 v53, v164, 0xbb000000, v53
	v_fma_f32 v154, v62, v62, v156
	v_fma_f32 v155, v58, v58, v157
	v_fmamk_f32 v49, v164, 0xbb000000, v49
	v_pk_add_f32 v[152:153], v[152:153], v[154:155]
	v_fmamk_f32 v55, v164, 0xbb000000, v55
	v_fmac_f32_e32 v52, 0xbb000000, v164
	v_fmamk_f32 v51, v164, 0xbb000000, v51
	v_fmac_f32_e32 v48, 0xbb000000, v164
	v_add_f32_e32 v160, v152, v153
	v_fmamk_f32 v54, v164, 0xbb000000, v54
	v_fmamk_f32 v50, v164, 0xbb000000, v50
	v_mul_f32_e32 v154, v53, v53
	v_mul_f32_e32 v155, v49, v49
	v_fma_f32 v152, v52, v52, v154
	v_fma_f32 v153, v48, v48, v155
	v_mul_f32_e32 v156, v55, v55
	v_mul_f32_e32 v157, v51, v51
	v_fmamk_f32 v45, v165, 0xbb000000, v45
	v_fma_f32 v154, v54, v54, v156
	v_fma_f32 v155, v50, v50, v157
	v_fmamk_f32 v41, v165, 0xbb000000, v41
	v_pk_add_f32 v[152:153], v[152:153], v[154:155]
	v_fmamk_f32 v47, v165, 0xbb000000, v47
	v_fmac_f32_e32 v44, 0xbb000000, v165
	v_fmamk_f32 v43, v165, 0xbb000000, v43
	v_fmac_f32_e32 v40, 0xbb000000, v165
	v_add_f32_e32 v163, v152, v153
	v_fmamk_f32 v46, v165, 0xbb000000, v46
	v_fmamk_f32 v42, v165, 0xbb000000, v42
	v_mul_f32_e32 v154, v45, v45
	v_mul_f32_e32 v155, v41, v41
	v_fma_f32 v152, v44, v44, v154
	v_fma_f32 v153, v40, v40, v155
	v_mul_f32_e32 v156, v47, v47
	v_mul_f32_e32 v157, v43, v43
	v_fmamk_f32 v37, v161, 0xbb000000, v37
	v_fma_f32 v154, v46, v46, v156
	v_fma_f32 v155, v42, v42, v157
	v_fmamk_f32 v33, v161, 0xbb000000, v33
	v_pk_add_f32 v[152:153], v[152:153], v[154:155]
	v_fmamk_f32 v39, v161, 0xbb000000, v39
	v_fmac_f32_e32 v36, 0xbb000000, v161
	v_fmamk_f32 v35, v161, 0xbb000000, v35
	v_fmac_f32_e32 v32, 0xbb000000, v161
	v_add_f32_e32 v164, v152, v153
	v_fmamk_f32 v38, v161, 0xbb000000, v38
	v_fmamk_f32 v34, v161, 0xbb000000, v34
	v_mul_f32_e32 v154, v37, v37
	v_mul_f32_e32 v155, v33, v33
	v_fma_f32 v152, v36, v36, v154
	v_fma_f32 v153, v32, v32, v155
; __global__ void __launch_bounds__(NWAVES * 64, 2) mk_fwd(Args args) {
;     ...
; #pragma unroll
;                     for (int k = 0; k < 8; ++k) { const float mu = sm[k] * (1.f / 512.f); a[k] = a[k] - mu; c[k] = c[k] - mu;
;                         sm[k] = ((a[k][0] * a[k][0] + a[k][1] * a[k][1]) + (a[k][2] * a[k][2] + a[k][3] * a[k][3])) + ((c[k][0] * c[k][0] + c[k][1] * c[k][1]) + (c[k][2] * c[k][2] + c[k][3] * c[k][3])); }
; #pragma unroll
;                     for (int o = 1; o < 64; o <<= 1) {
; #pragma unroll
;                         for (int k = 0; k < 8; ++k) sm[k] += __shfl_xor(sm[k], o); }
	v_mul_f32_e32 v156, v39, v39
	v_mul_f32_e32 v157, v35, v35
	v_fmamk_f32 v29, v158, 0xbb000000, v29
	v_fma_f32 v154, v38, v38, v156
	v_fma_f32 v155, v34, v34, v157
	v_fmamk_f32 v25, v158, 0xbb000000, v25
	v_pk_add_f32 v[152:153], v[152:153], v[154:155]
	v_fmamk_f32 v31, v158, 0xbb000000, v31
	v_fmac_f32_e32 v28, 0xbb000000, v158
	v_fmamk_f32 v27, v158, 0xbb000000, v27
	v_fmac_f32_e32 v24, 0xbb000000, v158
	v_add_f32_e32 v161, v152, v153
	v_fmamk_f32 v30, v158, 0xbb000000, v30
	v_fmamk_f32 v26, v158, 0xbb000000, v26
	v_mul_f32_e32 v154, v29, v29
	v_mul_f32_e32 v155, v25, v25
	v_fma_f32 v152, v28, v28, v154
	v_fma_f32 v153, v24, v24, v155
	v_mul_f32_e32 v156, v31, v31
	v_mul_f32_e32 v157, v27, v27
	v_fmamk_f32 v21, v162, 0xbb000000, v21
	v_fma_f32 v154, v30, v30, v156
	v_fma_f32 v155, v26, v26, v157
	v_fmamk_f32 v17, v162, 0xbb000000, v17
	v_pk_add_f32 v[152:153], v[152:153], v[154:155]
	v_fmamk_f32 v23, v162, 0xbb000000, v23
	v_fmac_f32_e32 v20, 0xbb000000, v162
	v_fmamk_f32 v19, v162, 0xbb000000, v19
	v_fmac_f32_e32 v16, 0xbb000000, v162
	v_add_f32_e32 v158, v152, v153
	v_fmamk_f32 v22, v162, 0xbb000000, v22
	v_fmamk_f32 v18, v162, 0xbb000000, v18
	v_mul_f32_e32 v154, v21, v21
	v_mul_f32_e32 v155, v17, v17
	v_fma_f32 v152, v20, v20, v154
	v_fma_f32 v153, v16, v16, v155
	v_mul_f32_e32 v156, v23, v23
	v_mul_f32_e32 v157, v19, v19
	s_add_i32 s4, s4, s14
	v_fma_f32 v154, v22, v22, v156
	v_fma_f32 v155, v18, v18, v157
	v_pk_add_f32 v[152:153], v[152:153], v[154:155]
	v_add_f32_e32 v152, v152, v153
	s_ashr_i32 s5, s4, 31
	s_waitcnt lgkmcnt(2)
	v_add_f32_dpp v81, v81, v81 quad_perm:[1,0,3,2] row_mask:0xf bank_mask:0xf
	v_add_f32_dpp v153, v159, v159 quad_perm:[1,0,3,2] row_mask:0xf bank_mask:0xf
	s_waitcnt lgkmcnt(1)
	v_add_f32_dpp v154, v160, v160 quad_perm:[1,0,3,2] row_mask:0xf bank_mask:0xf
	v_add_f32_dpp v155, v163, v163 quad_perm:[1,0,3,2] row_mask:0xf bank_mask:0xf
	s_waitcnt lgkmcnt(3)
	v_add_f32_dpp v156, v164, v164 quad_perm:[1,0,3,2] row_mask:0xf bank_mask:0xf
	s_waitcnt lgkmcnt(4)
	v_add_f32_dpp v158, v158, v158 quad_perm:[1,0,3,2] row_mask:0xf bank_mask:0xf
	s_waitcnt lgkmcnt(3)
	v_add_f32_dpp v152, v152, v152 quad_perm:[1,0,3,2] row_mask:0xf bank_mask:0xf
	s_waitcnt lgkmcnt(3)
	v_add_f32_dpp v153, v153, v153 quad_perm:[2,3,0,1] row_mask:0xf bank_mask:0xf
	s_waitcnt lgkmcnt(4)
	v_add_f32_dpp v157, v161, v161 quad_perm:[1,0,3,2] row_mask:0xf bank_mask:0xf
	s_waitcnt lgkmcnt(3)
	v_add_f32_dpp v81, v81, v81 quad_perm:[2,3,0,1] row_mask:0xf bank_mask:0xf
	s_waitcnt lgkmcnt(4)
	v_add_f32_dpp v155, v155, v155 quad_perm:[2,3,0,1] row_mask:0xf bank_mask:0xf
	s_waitcnt lgkmcnt(4)
	v_add_f32_dpp v154, v154, v154 quad_perm:[2,3,0,1] row_mask:0xf bank_mask:0xf
	s_waitcnt lgkmcnt(3)
	v_add_f32_dpp v158, v158, v158 quad_perm:[2,3,0,1] row_mask:0xf bank_mask:0xf
	s_waitcnt lgkmcnt(4)
	v_add_f32_dpp v157, v157, v157 quad_perm:[2,3,0,1] row_mask:0xf bank_mask:0xf
	s_waitcnt lgkmcnt(4)
	v_add_f32_dpp v156, v156, v156 quad_perm:[2,3,0,1] row_mask:0xf bank_mask:0xf
	s_waitcnt lgkmcnt(4)
	v_add_f32_dpp v81, v81, v81 row_half_mirror row_mask:0xf bank_mask:0xf
	s_waitcnt lgkmcnt(4)
	v_add_f32_dpp v152, v152, v152 quad_perm:[2,3,0,1] row_mask:0xf bank_mask:0xf
	s_waitcnt lgkmcnt(3)
	v_add_f32_dpp v155, v155, v155 row_half_mirror row_mask:0xf bank_mask:0xf
	s_waitcnt lgkmcnt(4)
	v_add_f32_dpp v154, v154, v154 row_half_mirror row_mask:0xf bank_mask:0xf
	s_waitcnt lgkmcnt(4)
	v_add_f32_dpp v153, v153, v153 row_half_mirror row_mask:0xf bank_mask:0xf
	s_waitcnt lgkmcnt(4)
	v_add_f32_dpp v157, v157, v157 row_half_mirror row_mask:0xf bank_mask:0xf
	s_waitcnt lgkmcnt(4)
	v_add_f32_dpp v156, v156, v156 row_half_mirror row_mask:0xf bank_mask:0xf
	s_waitcnt lgkmcnt(3)
	v_add_f32_dpp v81, v81, v81 row_mirror row_mask:0xf bank_mask:0xf
	s_waitcnt lgkmcnt(4)
	v_add_f32_dpp v152, v152, v152 row_half_mirror row_mask:0xf bank_mask:0xf
	s_waitcnt lgkmcnt(3)
	v_add_f32_dpp v158, v158, v158 row_half_mirror row_mask:0xf bank_mask:0xf
	s_waitcnt lgkmcnt(3)
	v_add_f32_dpp v154, v154, v154 row_mirror row_mask:0xf bank_mask:0xf
	s_waitcnt lgkmcnt(3)
	v_add_f32_dpp v153, v153, v153 row_mirror row_mask:0xf bank_mask:0xf
	s_waitcnt lgkmcnt(2)
	v_add_f32_dpp v157, v157, v157 row_mirror row_mask:0xf bank_mask:0xf
	v_mov_b32_e32 v163, v154
	s_nop 1
	v_permlane16_swap_b32_e32 v154, v163
	s_waitcnt lgkmcnt(4)
	v_add_f32_dpp v155, v155, v155 row_mirror row_mask:0xf bank_mask:0xf
	v_mov_b32_e32 v161, v81
	s_nop 1
	v_permlane16_swap_b32_e32 v81, v161
	s_waitcnt lgkmcnt(4)
	v_add_f32_dpp v152, v152, v152 row_mirror row_mask:0xf bank_mask:0xf
	s_waitcnt lgkmcnt(3)
	v_add_f32_dpp v158, v158, v158 row_mirror row_mask:0xf bank_mask:0xf
	s_waitcnt lgkmcnt(2)
	v_add_f32_e32 v154, v154, v163
	v_mov_b32_e32 v159, v155
	s_nop 1
	v_permlane16_swap_b32_e32 v155, v159
	v_mov_b32_e32 v163, v152
	s_nop 1
	v_permlane16_swap_b32_e32 v152, v163
	s_waitcnt lgkmcnt(3)
	v_add_f32_dpp v156, v156, v156 row_mirror row_mask:0xf bank_mask:0xf
	v_mov_b32_e32 v162, v153
	s_nop 1
	v_permlane16_swap_b32_e32 v153, v162
	v_mov_b32_e32 v160, v156
	s_nop 1
	v_permlane16_swap_b32_e32 v156, v160
	s_waitcnt lgkmcnt(4)
	v_add_f32_e32 v81, v81, v161
	v_mov_b32_e32 v161, v157
	s_nop 1
	v_permlane16_swap_b32_e32 v157, v161
	s_waitcnt lgkmcnt(4)
	v_add_f32_e32 v155, v155, v159
	s_waitcnt lgkmcnt(3)
	v_add_f32_e32 v159, v152, v163
	v_mov_b32_e32 v152, v81
	s_nop 1
	v_permlane32_swap_b32_e32 v81, v152
	s_waitcnt lgkmcnt(3)
	v_add_f32_e32 v153, v153, v162
	s_waitcnt lgkmcnt(2)
	v_add_f32_e32 v156, v156, v160
	v_mov_b32_e32 v160, v153
	s_nop 1
	v_permlane32_swap_b32_e32 v153, v160
	v_mov_b32_e32 v162, v158
	s_nop 1
	v_permlane16_swap_b32_e32 v158, v162
	s_waitcnt lgkmcnt(3)
; __device__ __forceinline__ unsigned pk2(float lo, float hi) { return pg8::cvt_pk_bf16(lo, hi); }
; __global__ void __launch_bounds__(NWAVES * 64, 2) mk_fwd(Args args) {
;     ...
; #pragma unroll
;                     for (int k = 0; k < 8; ++k) { const int tok = wave * 8 + k; const float rstd = 1.0f / sqrtf(sm[k] * (1.f / 512.f) + EPS);
;                         f32x4 x = a[k] * rstd * lg0 + lb0, y = c[k] * rstd * lg1 + lb1;
; #pragma unroll
;                         for (int e = 0; e < 4; ++e) { x[e] = x[e] * __builtin_amdgcn_rcpf(1.f + __builtin_amdgcn_exp2f(-LOG2E * x[e])); y[e] = y[e] * __builtin_amdgcn_rcpf(1.f + __builtin_amdgcn_exp2f(-LOG2E * y[e])); }
;                         bf16* orow = CAT + (size_t)(R0 + tok) * DM;
;                         *(v2u*)(orow + 4 * lane) = (v2u){pk2(x[0], x[1]), pk2(x[2], x[3])}; *(v2u*)(orow + 256 + 4 * lane) = (v2u){pk2(y[0], y[1]), pk2(y[2], y[3])}; }
	v_add_f32_e32 v157, v157, v161
	v_mov_b32_e32 v161, v154
	s_nop 1
	v_permlane32_swap_b32_e32 v154, v161
	s_waitcnt lgkmcnt(3)
	v_add_f32_e32 v81, v81, v152
	v_fmamk_f32 v81, v81, 0x3b000000, v176
	s_waitcnt lgkmcnt(2)
	v_add_f32_e32 v160, v153, v160
	v_mul_f32_e32 v153, 0x4f800000, v81
	v_cmp_gt_f32_e32 vcc, s11, v81
	s_waitcnt lgkmcnt(1)
	v_add_f32_e32 v158, v158, v162
	v_mov_b32_e32 v162, v155
	s_nop 1
	v_permlane32_swap_b32_e32 v155, v162
	v_cndmask_b32_e32 v81, v81, v153, vcc
	v_mov_b32_e32 v163, v156
	s_nop 1
	v_permlane32_swap_b32_e32 v156, v163
	s_waitcnt lgkmcnt(2)
	v_add_f32_e32 v161, v154, v161
	v_sqrt_f32_e32 v154, v81
	s_waitcnt lgkmcnt(1)
	v_add_f32_e32 v155, v155, v162
	v_mov_b32_e32 v152, v157
	s_nop 1
	v_permlane32_swap_b32_e32 v157, v152
	s_waitcnt lgkmcnt(1)
	v_add_f32_e32 v156, v156, v163
	v_add_u32_e32 v162, -1, v154
	v_fma_f32 v163, -v162, v154, v81
	v_cmp_ge_f32_e64 s[2:3], 0, v163
	v_add_u32_e32 v163, 1, v154
	s_waitcnt lgkmcnt(0)
	v_add_f32_e32 v153, v157, v152
	v_cndmask_b32_e64 v162, v154, v162, s[2:3]
	v_fma_f32 v154, -v163, v154, v81
	v_cmp_lt_f32_e64 s[2:3], 0, v154
	v_mov_b32_e32 v157, v159
	s_nop 1
	v_permlane32_swap_b32_e32 v159, v157
	v_mov_b32_e32 v152, v158
	s_nop 1
	v_permlane32_swap_b32_e32 v158, v152
	v_cndmask_b32_e64 v154, v162, v163, s[2:3]
	v_mul_f32_e32 v162, 0x37800000, v154
	v_cndmask_b32_e32 v154, v154, v162, vcc
	v_cmp_class_f32_e32 vcc, v81, v177
	s_waitcnt lgkmcnt(0)
	v_add_f32_e32 v152, v158, v152
	v_cndmask_b32_e32 v154, v154, v81, vcc
	v_div_scale_f32 v162, s[2:3], v154, v154, 1.0
	v_rcp_f32_e32 v163, v162
	v_add_f32_e32 v81, v159, v157
	s_lshl_b64 s[2:3], s[4:5], 11
	s_add_i32 s5, s6, s40
	v_fma_f32 v157, -v162, v163, 1.0
	v_fmac_f32_e32 v163, v157, v163
	v_div_scale_f32 v157, vcc, 1.0, v154, 1.0
	v_mul_f32_e32 v158, v157, v163
	v_fma_f32 v159, -v162, v158, v157
	v_fmac_f32_e32 v158, v159, v163
	v_fma_f32 v157, -v162, v158, v157
	v_div_fmas_f32 v157, v157, v163, v158
	v_div_fixup_f32 v154, v157, v154, 1.0
	v_pk_mul_f32 v[76:77], v[154:155], v[76:77] op_sel_hi:[0,1]
	v_pk_fma_f32 v[76:77], v[0:1], v[76:77], v[8:9]
	v_pk_mul_f32 v[72:73], v[154:155], v[72:73] op_sel_hi:[0,1]
	v_mul_f32_e32 v157, 0xbfb8aa3b, v76
	v_exp_f32_e32 v157, v157
	v_pk_fma_f32 v[72:73], v[4:5], v[72:73], v[12:13]
	v_pk_mul_f32 v[78:79], v[154:155], v[78:79] op_sel_hi:[0,1]
	v_pk_mul_f32 v[74:75], v[154:155], v[74:75] op_sel_hi:[0,1]
	v_add_f32_e32 v154, 1.0, v157
	v_mul_f32_e32 v157, 0xbfb8aa3b, v72
	v_mul_f32_e32 v158, 0xbfb8aa3b, v77
	v_exp_f32_e32 v157, v157
	v_exp_f32_e32 v158, v158
	v_mul_f32_e32 v159, 0xbfb8aa3b, v73
	v_rcp_f32_e32 v154, v154
	v_add_f32_e32 v157, 1.0, v157
	v_add_f32_e32 v158, 1.0, v158
	v_rcp_f32_e32 v157, v157
	v_rcp_f32_e32 v158, v158
	v_exp_f32_e32 v159, v159
	v_pk_fma_f32 v[78:79], v[2:3], v[78:79], v[10:11]
	v_pk_fma_f32 v[74:75], v[6:7], v[74:75], v[14:15]
	v_mul_f32_e32 v76, v76, v154
	v_mul_f32_e32 v154, v72, v157
	v_mul_f32_e32 v72, v77, v158
	v_add_f32_e32 v77, 1.0, v159
	v_mul_f32_e32 v157, 0xbfb8aa3b, v78
	v_mul_f32_e32 v158, 0xbfb8aa3b, v74
	v_rcp_f32_e32 v77, v77
	v_exp_f32_e32 v157, v157
	v_exp_f32_e32 v158, v158
	v_mul_f32_e32 v159, 0xbfb8aa3b, v75
	v_mul_f32_e32 v77, v73, v77
	v_add_f32_e32 v73, 1.0, v157
	v_add_f32_e32 v157, 1.0, v158
	v_mul_f32_e32 v158, 0xbfb8aa3b, v79
	v_exp_f32_e32 v158, v158
	v_exp_f32_e32 v159, v159
	v_rcp_f32_e32 v73, v73
	v_rcp_f32_e32 v157, v157
	v_add_f32_e32 v158, 1.0, v158
	v_add_f32_e32 v159, 1.0, v159
	v_rcp_f32_e32 v158, v158
	v_rcp_f32_e32 v159, v159
	v_mul_f32_e32 v73, v78, v73
	v_mul_f32_e32 v78, v74, v157
	v_mul_f32_e32 v74, v79, v158
	v_mul_f32_e32 v79, v75, v159
	v_fmamk_f32 v75, v160, 0x3b000000, v176
	v_cvt_pk_bf16_f32 v72, v76, v72
	v_mul_f32_e32 v76, 0x4f800000, v75
	v_cmp_gt_f32_e32 vcc, s11, v75
	v_cvt_pk_bf16_f32 v73, v73, v74
	s_nop 1
	v_cndmask_b32_e32 v76, v75, v76, vcc
	v_sqrt_f32_e32 v157, v76
	v_lshl_add_u64 v[74:75], v[148:149], 0, s[2:3]
	flat_store_dwordx2 v[74:75], v[72:73]
	v_add_u32_e32 v72, -1, v157
	v_fma_f32 v73, -v72, v157, v76
	v_cmp_ge_f32_e64 s[2:3], 0, v73
	v_add_u32_e32 v73, 1, v157
	s_nop 0
	v_cndmask_b32_e64 v72, v157, v72, s[2:3]
	v_fma_f32 v157, -v73, v157, v76
	v_cmp_lt_f32_e64 s[2:3], 0, v157
	s_nop 1
	v_cndmask_b32_e64 v72, v72, v73, s[2:3]
	v_mul_f32_e32 v73, 0x37800000, v72
	v_cndmask_b32_e32 v72, v72, v73, vcc
	v_cmp_class_f32_e32 vcc, v76, v177
	s_nop 1
	v_cndmask_b32_e32 v76, v72, v76, vcc
	v_div_scale_f32 v157, s[2:3], v76, v76, 1.0
	v_rcp_f32_e32 v158, v157
	v_cvt_pk_bf16_f32 v72, v154, v77
	v_cvt_pk_bf16_f32 v73, v78, v79
	flat_store_dwordx2 v[74:75], v[72:73] offset:512
	v_fma_f32 v72, -v157, v158, 1.0
	v_fmac_f32_e32 v158, v72, v158
	v_div_scale_f32 v72, vcc, 1.0, v76, 1.0
	v_mul_f32_e32 v73, v72, v158
	v_fma_f32 v74, -v157, v73, v72
	v_fmac_f32_e32 v73, v74, v158
	v_fma_f32 v72, -v157, v73, v72
	v_div_fmas_f32 v72, v72, v158, v73
	v_div_fixup_f32 v72, v72, v76, 1.0
	v_pk_mul_f32 v[68:69], v[72:73], v[68:69] op_sel_hi:[0,1]
	v_pk_fma_f32 v[68:69], v[0:1], v[68:69], v[8:9]
	v_pk_mul_f32 v[70:71], v[72:73], v[70:71] op_sel_hi:[0,1]
	v_pk_mul_f32 v[64:65], v[72:73], v[64:65] op_sel_hi:[0,1]
	v_mul_f32_e32 v73, 0xbfb8aa3b, v68
	v_exp_f32_e32 v73, v73
	v_pk_fma_f32 v[64:65], v[4:5], v[64:65], v[12:13]
	v_mul_f32_e32 v74, 0xbfb8aa3b, v69
	v_exp_f32_e32 v74, v74
	v_pk_mul_f32 v[66:67], v[72:73], v[66:67] op_sel_hi:[0,1]
	v_add_f32_e32 v72, 1.0, v73
	v_mul_f32_e32 v73, 0xbfb8aa3b, v64
	v_exp_f32_e32 v73, v73
	v_add_f32_e32 v74, 1.0, v74
	v_mul_f32_e32 v75, 0xbfb8aa3b, v65
	v_rcp_f32_e32 v72, v72
	v_add_f32_e32 v73, 1.0, v73
	v_rcp_f32_e32 v73, v73
	v_rcp_f32_e32 v74, v74
	v_exp_f32_e32 v75, v75
; __device__ __forceinline__ unsigned pk2(float lo, float hi) { return pg8::cvt_pk_bf16(lo, hi); }
; __global__ void __launch_bounds__(NWAVES * 64, 2) mk_fwd(Args args) {
;     ...
;                     for (int k = 0; k < 8; ++k) { const int tok = wave * 8 + k; const float rstd = 1.0f / sqrtf(sm[k] * (1.f / 512.f) + EPS);
;                         f32x4 x = a[k] * rstd * lg0 + lb0, y = c[k] * rstd * lg1 + lb1;
; #pragma unroll
;                         for (int e = 0; e < 4; ++e) { x[e] = x[e] * __builtin_amdgcn_rcpf(1.f + __builtin_amdgcn_exp2f(-LOG2E * x[e])); y[e] = y[e] * __builtin_amdgcn_rcpf(1.f + __builtin_amdgcn_exp2f(-LOG2E * y[e])); }
;                         bf16* orow = CAT + (size_t)(R0 + tok) * DM;
;                         *(v2u*)(orow + 4 * lane) = (v2u){pk2(x[0], x[1]), pk2(x[2], x[3])}; *(v2u*)(orow + 256 + 4 * lane) = (v2u){pk2(y[0], y[1]), pk2(y[2], y[3])}; }
	v_pk_fma_f32 v[70:71], v[2:3], v[70:71], v[10:11]
	v_pk_fma_f32 v[66:67], v[6:7], v[66:67], v[14:15]
	v_mul_f32_e32 v68, v68, v72
	v_mul_f32_e32 v72, v64, v73
	v_mul_f32_e32 v64, v69, v74
	v_add_f32_e32 v69, 1.0, v75
	v_mul_f32_e32 v73, 0xbfb8aa3b, v70
	v_mul_f32_e32 v74, 0xbfb8aa3b, v66
	v_rcp_f32_e32 v69, v69
	v_exp_f32_e32 v73, v73
	v_exp_f32_e32 v74, v74
	v_mul_f32_e32 v75, 0xbfb8aa3b, v67
	v_mul_f32_e32 v69, v65, v69
	v_add_f32_e32 v65, 1.0, v73
	v_add_f32_e32 v73, 1.0, v74
	v_mul_f32_e32 v74, 0xbfb8aa3b, v71
	v_exp_f32_e32 v74, v74
	v_exp_f32_e32 v75, v75
	v_rcp_f32_e32 v65, v65
	v_rcp_f32_e32 v73, v73
	v_add_f32_e32 v74, 1.0, v74
	v_add_f32_e32 v75, 1.0, v75
	v_rcp_f32_e32 v74, v74
	v_rcp_f32_e32 v75, v75
	v_mul_f32_e32 v65, v70, v65
	v_mul_f32_e32 v70, v66, v73
	v_mul_f32_e32 v66, v71, v74
	v_mul_f32_e32 v71, v67, v75
	v_fmamk_f32 v67, v161, 0x3b000000, v176
	v_cvt_pk_bf16_f32 v64, v68, v64
	v_mul_f32_e32 v68, 0x4f800000, v67
	v_cmp_gt_f32_e32 vcc, s11, v67
	s_or_b32 s2, s4, 1
	s_ashr_i32 s3, s2, 31
	v_cndmask_b32_e32 v68, v67, v68, vcc
	v_sqrt_f32_e32 v73, v68
	s_lshl_b64 s[2:3], s[2:3], 11
	v_cvt_pk_bf16_f32 v65, v65, v66
	v_lshl_add_u64 v[66:67], v[148:149], 0, s[2:3]
	flat_store_dwordx2 v[66:67], v[64:65]
	v_add_u32_e32 v64, -1, v73
	v_fma_f32 v65, -v64, v73, v68
	v_cmp_ge_f32_e64 s[2:3], 0, v65
	v_add_u32_e32 v65, 1, v73
	s_nop 0
	v_cndmask_b32_e64 v64, v73, v64, s[2:3]
	v_fma_f32 v73, -v65, v73, v68
	v_cmp_lt_f32_e64 s[2:3], 0, v73
	s_nop 1
	v_cndmask_b32_e64 v64, v64, v65, s[2:3]
	v_mul_f32_e32 v65, 0x37800000, v64
	v_cndmask_b32_e32 v64, v64, v65, vcc
	v_cmp_class_f32_e32 vcc, v68, v177
	s_nop 1
	v_cndmask_b32_e32 v68, v64, v68, vcc
	v_div_scale_f32 v73, s[2:3], v68, v68, 1.0
	v_rcp_f32_e32 v74, v73
	v_cvt_pk_bf16_f32 v64, v72, v69
	v_cvt_pk_bf16_f32 v65, v70, v71
	flat_store_dwordx2 v[66:67], v[64:65] offset:512
	v_fma_f32 v64, -v73, v74, 1.0
	v_fmac_f32_e32 v74, v64, v74
	v_div_scale_f32 v64, vcc, 1.0, v68, 1.0
	v_mul_f32_e32 v65, v64, v74
	v_fma_f32 v66, -v73, v65, v64
	v_fmac_f32_e32 v65, v66, v74
	v_fma_f32 v64, -v73, v65, v64
	v_div_fmas_f32 v64, v64, v74, v65
	v_div_fixup_f32 v64, v64, v68, 1.0
	v_pk_mul_f32 v[60:61], v[64:65], v[60:61] op_sel_hi:[0,1]
	v_pk_fma_f32 v[60:61], v[0:1], v[60:61], v[8:9]
	v_pk_mul_f32 v[62:63], v[64:65], v[62:63] op_sel_hi:[0,1]
	v_pk_mul_f32 v[56:57], v[64:65], v[56:57] op_sel_hi:[0,1]
	v_mul_f32_e32 v65, 0xbfb8aa3b, v60
	v_exp_f32_e32 v65, v65
	v_pk_fma_f32 v[56:57], v[4:5], v[56:57], v[12:13]
	v_mul_f32_e32 v66, 0xbfb8aa3b, v61
	v_exp_f32_e32 v66, v66
	v_pk_mul_f32 v[58:59], v[64:65], v[58:59] op_sel_hi:[0,1]
	v_add_f32_e32 v64, 1.0, v65
	v_mul_f32_e32 v65, 0xbfb8aa3b, v56
	v_exp_f32_e32 v65, v65
	v_add_f32_e32 v66, 1.0, v66
	v_mul_f32_e32 v67, 0xbfb8aa3b, v57
	v_rcp_f32_e32 v64, v64
	v_add_f32_e32 v65, 1.0, v65
	v_rcp_f32_e32 v65, v65
	v_rcp_f32_e32 v66, v66
	v_exp_f32_e32 v67, v67
	v_pk_fma_f32 v[62:63], v[2:3], v[62:63], v[10:11]
	v_pk_fma_f32 v[58:59], v[6:7], v[58:59], v[14:15]
	v_mul_f32_e32 v60, v60, v64
	v_mul_f32_e32 v64, v56, v65
	v_mul_f32_e32 v56, v61, v66
	v_add_f32_e32 v61, 1.0, v67
	v_mul_f32_e32 v65, 0xbfb8aa3b, v62
	v_mul_f32_e32 v66, 0xbfb8aa3b, v58
	v_rcp_f32_e32 v61, v61
	v_exp_f32_e32 v65, v65
	v_exp_f32_e32 v66, v66
	v_mul_f32_e32 v67, 0xbfb8aa3b, v59
	v_mul_f32_e32 v61, v57, v61
	v_add_f32_e32 v57, 1.0, v65
	v_add_f32_e32 v65, 1.0, v66
	v_mul_f32_e32 v66, 0xbfb8aa3b, v63
	v_exp_f32_e32 v66, v66
	v_exp_f32_e32 v67, v67
	v_rcp_f32_e32 v57, v57
	v_rcp_f32_e32 v65, v65
	v_add_f32_e32 v66, 1.0, v66
	v_add_f32_e32 v67, 1.0, v67
	v_rcp_f32_e32 v66, v66
	v_rcp_f32_e32 v67, v67
	v_mul_f32_e32 v57, v62, v57
	v_mul_f32_e32 v62, v58, v65
	v_mul_f32_e32 v58, v63, v66
	v_mul_f32_e32 v63, v59, v67
	v_fmamk_f32 v59, v155, 0x3b000000, v176
	v_cvt_pk_bf16_f32 v56, v60, v56
	v_mul_f32_e32 v60, 0x4f800000, v59
	v_cmp_gt_f32_e32 vcc, s11, v59
	s_or_b32 s2, s4, 2
	s_ashr_i32 s3, s2, 31
	v_cndmask_b32_e32 v60, v59, v60, vcc
	v_sqrt_f32_e32 v65, v60
	s_lshl_b64 s[2:3], s[2:3], 11
	v_cvt_pk_bf16_f32 v57, v57, v58
	v_lshl_add_u64 v[58:59], v[148:149], 0, s[2:3]
	flat_store_dwordx2 v[58:59], v[56:57]
	v_add_u32_e32 v56, -1, v65
	v_fma_f32 v57, -v56, v65, v60
	v_cmp_ge_f32_e64 s[2:3], 0, v57
	v_add_u32_e32 v57, 1, v65
	s_nop 0
	v_cndmask_b32_e64 v56, v65, v56, s[2:3]
	v_fma_f32 v65, -v57, v65, v60
	v_cmp_lt_f32_e64 s[2:3], 0, v65
	s_nop 1
	v_cndmask_b32_e64 v56, v56, v57, s[2:3]
	v_mul_f32_e32 v57, 0x37800000, v56
	v_cndmask_b32_e32 v56, v56, v57, vcc
	v_cmp_class_f32_e32 vcc, v60, v177
	s_nop 1
	v_cndmask_b32_e32 v60, v56, v60, vcc
	v_div_scale_f32 v65, s[2:3], v60, v60, 1.0
	v_rcp_f32_e32 v66, v65
	v_cvt_pk_bf16_f32 v56, v64, v61
	v_cvt_pk_bf16_f32 v57, v62, v63
	flat_store_dwordx2 v[58:59], v[56:57] offset:512
	v_fma_f32 v56, -v65, v66, 1.0
	v_fmac_f32_e32 v66, v56, v66
	v_div_scale_f32 v56, vcc, 1.0, v60, 1.0
	v_mul_f32_e32 v57, v56, v66
	v_fma_f32 v58, -v65, v57, v56
	v_fmac_f32_e32 v57, v58, v66
	v_fma_f32 v56, -v65, v57, v56
	v_div_fmas_f32 v56, v56, v66, v57
	v_div_fixup_f32 v56, v56, v60, 1.0
	v_pk_mul_f32 v[52:53], v[56:57], v[52:53] op_sel_hi:[0,1]
	v_pk_fma_f32 v[52:53], v[0:1], v[52:53], v[8:9]
	v_pk_mul_f32 v[54:55], v[56:57], v[54:55] op_sel_hi:[0,1]
	v_pk_mul_f32 v[48:49], v[56:57], v[48:49] op_sel_hi:[0,1]
	v_mul_f32_e32 v57, 0xbfb8aa3b, v52
	v_exp_f32_e32 v57, v57
	v_pk_fma_f32 v[48:49], v[4:5], v[48:49], v[12:13]
	v_mul_f32_e32 v58, 0xbfb8aa3b, v53
	v_exp_f32_e32 v58, v58
	v_pk_mul_f32 v[50:51], v[56:57], v[50:51] op_sel_hi:[0,1]
	v_add_f32_e32 v56, 1.0, v57
	v_mul_f32_e32 v57, 0xbfb8aa3b, v48
	v_exp_f32_e32 v57, v57
	v_add_f32_e32 v58, 1.0, v58
	v_mul_f32_e32 v59, 0xbfb8aa3b, v49
; __device__ __forceinline__ unsigned pk2(float lo, float hi) { return pg8::cvt_pk_bf16(lo, hi); }
; __global__ void __launch_bounds__(NWAVES * 64, 2) mk_fwd(Args args) {
;     ...
;                     for (int k = 0; k < 8; ++k) { const int tok = wave * 8 + k; const float rstd = 1.0f / sqrtf(sm[k] * (1.f / 512.f) + EPS);
;                         f32x4 x = a[k] * rstd * lg0 + lb0, y = c[k] * rstd * lg1 + lb1;
; #pragma unroll
;                         for (int e = 0; e < 4; ++e) { x[e] = x[e] * __builtin_amdgcn_rcpf(1.f + __builtin_amdgcn_exp2f(-LOG2E * x[e])); y[e] = y[e] * __builtin_amdgcn_rcpf(1.f + __builtin_amdgcn_exp2f(-LOG2E * y[e])); }
;                         bf16* orow = CAT + (size_t)(R0 + tok) * DM;
;                         *(v2u*)(orow + 4 * lane) = (v2u){pk2(x[0], x[1]), pk2(x[2], x[3])}; *(v2u*)(orow + 256 + 4 * lane) = (v2u){pk2(y[0], y[1]), pk2(y[2], y[3])}; }
	v_rcp_f32_e32 v56, v56
	v_add_f32_e32 v57, 1.0, v57
	v_rcp_f32_e32 v57, v57
	v_rcp_f32_e32 v58, v58
	v_exp_f32_e32 v59, v59
	v_pk_fma_f32 v[54:55], v[2:3], v[54:55], v[10:11]
	v_pk_fma_f32 v[50:51], v[6:7], v[50:51], v[14:15]
	v_mul_f32_e32 v52, v52, v56
	v_mul_f32_e32 v56, v48, v57
	v_mul_f32_e32 v48, v53, v58
	v_add_f32_e32 v53, 1.0, v59
	v_mul_f32_e32 v57, 0xbfb8aa3b, v54
	v_mul_f32_e32 v58, 0xbfb8aa3b, v50
	v_rcp_f32_e32 v53, v53
	v_exp_f32_e32 v57, v57
	v_exp_f32_e32 v58, v58
	v_mul_f32_e32 v59, 0xbfb8aa3b, v51
	v_mul_f32_e32 v53, v49, v53
	v_add_f32_e32 v49, 1.0, v57
	v_add_f32_e32 v57, 1.0, v58
	v_mul_f32_e32 v58, 0xbfb8aa3b, v55
	v_exp_f32_e32 v58, v58
	v_exp_f32_e32 v59, v59
	v_rcp_f32_e32 v49, v49
	v_rcp_f32_e32 v57, v57
	v_add_f32_e32 v58, 1.0, v58
	v_add_f32_e32 v59, 1.0, v59
	v_rcp_f32_e32 v58, v58
	v_rcp_f32_e32 v59, v59
	v_mul_f32_e32 v49, v54, v49
	v_mul_f32_e32 v54, v50, v57
	v_mul_f32_e32 v50, v55, v58
	v_mul_f32_e32 v55, v51, v59
	v_fmamk_f32 v51, v156, 0x3b000000, v176
	v_cvt_pk_bf16_f32 v48, v52, v48
	v_mul_f32_e32 v52, 0x4f800000, v51
	v_cmp_gt_f32_e32 vcc, s11, v51
	s_or_b32 s2, s4, 3
	s_ashr_i32 s3, s2, 31
	v_cndmask_b32_e32 v52, v51, v52, vcc
	v_sqrt_f32_e32 v57, v52
	s_lshl_b64 s[2:3], s[2:3], 11
	v_cvt_pk_bf16_f32 v49, v49, v50
	v_lshl_add_u64 v[50:51], v[148:149], 0, s[2:3]
	flat_store_dwordx2 v[50:51], v[48:49]
	v_add_u32_e32 v48, -1, v57
	v_fma_f32 v49, -v48, v57, v52
	v_cmp_ge_f32_e64 s[2:3], 0, v49
	v_add_u32_e32 v49, 1, v57
	s_nop 0
	v_cndmask_b32_e64 v48, v57, v48, s[2:3]
	v_fma_f32 v57, -v49, v57, v52
	v_cmp_lt_f32_e64 s[2:3], 0, v57
	s_nop 1
	v_cndmask_b32_e64 v48, v48, v49, s[2:3]
	v_mul_f32_e32 v49, 0x37800000, v48
	v_cndmask_b32_e32 v48, v48, v49, vcc
	v_cmp_class_f32_e32 vcc, v52, v177
	s_nop 1
	v_cndmask_b32_e32 v52, v48, v52, vcc
	v_div_scale_f32 v57, s[2:3], v52, v52, 1.0
	v_rcp_f32_e32 v58, v57
	v_cvt_pk_bf16_f32 v48, v56, v53
	v_cvt_pk_bf16_f32 v49, v54, v55
	flat_store_dwordx2 v[50:51], v[48:49] offset:512
	v_fma_f32 v48, -v57, v58, 1.0
	v_fmac_f32_e32 v58, v48, v58
	v_div_scale_f32 v48, vcc, 1.0, v52, 1.0
	v_mul_f32_e32 v49, v48, v58
	v_fma_f32 v50, -v57, v49, v48
	v_fmac_f32_e32 v49, v50, v58
	v_fma_f32 v48, -v57, v49, v48
	v_div_fmas_f32 v48, v48, v58, v49
	v_div_fixup_f32 v48, v48, v52, 1.0
	v_pk_mul_f32 v[44:45], v[48:49], v[44:45] op_sel_hi:[0,1]
	v_pk_fma_f32 v[44:45], v[0:1], v[44:45], v[8:9]
	v_pk_mul_f32 v[46:47], v[48:49], v[46:47] op_sel_hi:[0,1]
	v_pk_mul_f32 v[40:41], v[48:49], v[40:41] op_sel_hi:[0,1]
	v_mul_f32_e32 v49, 0xbfb8aa3b, v44
	v_exp_f32_e32 v49, v49
	v_pk_fma_f32 v[40:41], v[4:5], v[40:41], v[12:13]
	v_mul_f32_e32 v50, 0xbfb8aa3b, v45
	v_exp_f32_e32 v50, v50
	v_pk_mul_f32 v[42:43], v[48:49], v[42:43] op_sel_hi:[0,1]
	v_add_f32_e32 v48, 1.0, v49
	v_mul_f32_e32 v49, 0xbfb8aa3b, v40
	v_exp_f32_e32 v49, v49
	v_add_f32_e32 v50, 1.0, v50
	v_mul_f32_e32 v51, 0xbfb8aa3b, v41
	v_rcp_f32_e32 v48, v48
	v_add_f32_e32 v49, 1.0, v49
	v_rcp_f32_e32 v49, v49
	v_rcp_f32_e32 v50, v50
	v_exp_f32_e32 v51, v51
	v_pk_fma_f32 v[46:47], v[2:3], v[46:47], v[10:11]
	v_pk_fma_f32 v[42:43], v[6:7], v[42:43], v[14:15]
	v_mul_f32_e32 v44, v44, v48
	v_mul_f32_e32 v48, v40, v49
	v_mul_f32_e32 v40, v45, v50
	v_add_f32_e32 v45, 1.0, v51
	v_mul_f32_e32 v49, 0xbfb8aa3b, v46
	v_mul_f32_e32 v50, 0xbfb8aa3b, v42
	v_rcp_f32_e32 v45, v45
	v_exp_f32_e32 v49, v49
	v_exp_f32_e32 v50, v50
	v_mul_f32_e32 v51, 0xbfb8aa3b, v43
	v_mul_f32_e32 v45, v41, v45
	v_add_f32_e32 v41, 1.0, v49
	v_add_f32_e32 v49, 1.0, v50
	v_mul_f32_e32 v50, 0xbfb8aa3b, v47
	v_exp_f32_e32 v50, v50
	v_exp_f32_e32 v51, v51
	v_rcp_f32_e32 v41, v41
	v_rcp_f32_e32 v49, v49
	v_add_f32_e32 v50, 1.0, v50
	v_add_f32_e32 v51, 1.0, v51
	v_rcp_f32_e32 v50, v50
	v_rcp_f32_e32 v51, v51
	v_mul_f32_e32 v41, v46, v41
	v_mul_f32_e32 v46, v42, v49
	v_mul_f32_e32 v42, v47, v50
	v_mul_f32_e32 v47, v43, v51
	v_fmamk_f32 v43, v153, 0x3b000000, v176
	v_cvt_pk_bf16_f32 v40, v44, v40
	v_mul_f32_e32 v44, 0x4f800000, v43
	v_cmp_gt_f32_e32 vcc, s11, v43
	s_or_b32 s2, s4, 4
	s_ashr_i32 s3, s2, 31
	v_cndmask_b32_e32 v44, v43, v44, vcc
	v_sqrt_f32_e32 v49, v44
	s_lshl_b64 s[2:3], s[2:3], 11
	v_cvt_pk_bf16_f32 v41, v41, v42
	v_lshl_add_u64 v[42:43], v[148:149], 0, s[2:3]
	flat_store_dwordx2 v[42:43], v[40:41]
	v_add_u32_e32 v40, -1, v49
	v_fma_f32 v41, -v40, v49, v44
	v_cmp_ge_f32_e64 s[2:3], 0, v41
	v_add_u32_e32 v41, 1, v49
	s_nop 0
	v_cndmask_b32_e64 v40, v49, v40, s[2:3]
	v_fma_f32 v49, -v41, v49, v44
	v_cmp_lt_f32_e64 s[2:3], 0, v49
	s_nop 1
	v_cndmask_b32_e64 v40, v40, v41, s[2:3]
	v_mul_f32_e32 v41, 0x37800000, v40
	v_cndmask_b32_e32 v40, v40, v41, vcc
	v_cmp_class_f32_e32 vcc, v44, v177
	s_nop 1
	v_cndmask_b32_e32 v44, v40, v44, vcc
	v_div_scale_f32 v49, s[2:3], v44, v44, 1.0
	v_rcp_f32_e32 v50, v49
	v_cvt_pk_bf16_f32 v40, v48, v45
	v_cvt_pk_bf16_f32 v41, v46, v47
	flat_store_dwordx2 v[42:43], v[40:41] offset:512
	v_fma_f32 v40, -v49, v50, 1.0
	v_fmac_f32_e32 v50, v40, v50
	v_div_scale_f32 v40, vcc, 1.0, v44, 1.0
	v_mul_f32_e32 v41, v40, v50
	v_fma_f32 v42, -v49, v41, v40
	v_fmac_f32_e32 v41, v42, v50
	v_fma_f32 v40, -v49, v41, v40
	v_div_fmas_f32 v40, v40, v50, v41
	v_div_fixup_f32 v40, v40, v44, 1.0
	v_pk_mul_f32 v[36:37], v[40:41], v[36:37] op_sel_hi:[0,1]
	v_pk_fma_f32 v[36:37], v[0:1], v[36:37], v[8:9]
	v_pk_mul_f32 v[38:39], v[40:41], v[38:39] op_sel_hi:[0,1]
	v_pk_mul_f32 v[32:33], v[40:41], v[32:33] op_sel_hi:[0,1]
	v_mul_f32_e32 v41, 0xbfb8aa3b, v36
	v_exp_f32_e32 v41, v41
	v_pk_fma_f32 v[32:33], v[4:5], v[32:33], v[12:13]
	v_mul_f32_e32 v42, 0xbfb8aa3b, v37
	v_exp_f32_e32 v42, v42
	v_pk_mul_f32 v[34:35], v[40:41], v[34:35] op_sel_hi:[0,1]
; __device__ __forceinline__ unsigned pk2(float lo, float hi) { return pg8::cvt_pk_bf16(lo, hi); }
; __global__ void __launch_bounds__(NWAVES * 64, 2) mk_fwd(Args args) {
;     ...
;                     for (int k = 0; k < 8; ++k) { const int tok = wave * 8 + k; const float rstd = 1.0f / sqrtf(sm[k] * (1.f / 512.f) + EPS);
;                         f32x4 x = a[k] * rstd * lg0 + lb0, y = c[k] * rstd * lg1 + lb1;
; #pragma unroll
;                         for (int e = 0; e < 4; ++e) { x[e] = x[e] * __builtin_amdgcn_rcpf(1.f + __builtin_amdgcn_exp2f(-LOG2E * x[e])); y[e] = y[e] * __builtin_amdgcn_rcpf(1.f + __builtin_amdgcn_exp2f(-LOG2E * y[e])); }
;                         bf16* orow = CAT + (size_t)(R0 + tok) * DM;
;                         *(v2u*)(orow + 4 * lane) = (v2u){pk2(x[0], x[1]), pk2(x[2], x[3])}; *(v2u*)(orow + 256 + 4 * lane) = (v2u){pk2(y[0], y[1]), pk2(y[2], y[3])}; }
	v_add_f32_e32 v40, 1.0, v41
	v_mul_f32_e32 v41, 0xbfb8aa3b, v32
	v_exp_f32_e32 v41, v41
	v_add_f32_e32 v42, 1.0, v42
	v_mul_f32_e32 v43, 0xbfb8aa3b, v33
	v_rcp_f32_e32 v40, v40
	v_add_f32_e32 v41, 1.0, v41
	v_rcp_f32_e32 v41, v41
	v_rcp_f32_e32 v42, v42
	v_exp_f32_e32 v43, v43
	v_pk_fma_f32 v[38:39], v[2:3], v[38:39], v[10:11]
	v_pk_fma_f32 v[34:35], v[6:7], v[34:35], v[14:15]
	v_mul_f32_e32 v36, v36, v40
	v_mul_f32_e32 v40, v32, v41
	v_mul_f32_e32 v32, v37, v42
	v_add_f32_e32 v37, 1.0, v43
	v_mul_f32_e32 v41, 0xbfb8aa3b, v38
	v_mul_f32_e32 v42, 0xbfb8aa3b, v34
	v_rcp_f32_e32 v37, v37
	v_exp_f32_e32 v41, v41
	v_exp_f32_e32 v42, v42
	v_mul_f32_e32 v43, 0xbfb8aa3b, v35
	v_mul_f32_e32 v37, v33, v37
	v_add_f32_e32 v33, 1.0, v41
	v_add_f32_e32 v41, 1.0, v42
	v_mul_f32_e32 v42, 0xbfb8aa3b, v39
	v_exp_f32_e32 v42, v42
	v_exp_f32_e32 v43, v43
	v_rcp_f32_e32 v33, v33
	v_rcp_f32_e32 v41, v41
	v_add_f32_e32 v42, 1.0, v42
	v_add_f32_e32 v43, 1.0, v43
	v_rcp_f32_e32 v42, v42
	v_rcp_f32_e32 v43, v43
	v_mul_f32_e32 v33, v38, v33
	v_mul_f32_e32 v38, v34, v41
	v_mul_f32_e32 v34, v39, v42
	v_mul_f32_e32 v39, v35, v43
	v_fmamk_f32 v35, v152, 0x3b000000, v176
	v_cvt_pk_bf16_f32 v32, v36, v32
	v_mul_f32_e32 v36, 0x4f800000, v35
	v_cmp_gt_f32_e32 vcc, s11, v35
	s_or_b32 s2, s4, 5
	s_ashr_i32 s3, s2, 31
	v_cndmask_b32_e32 v36, v35, v36, vcc
	v_sqrt_f32_e32 v41, v36
	s_lshl_b64 s[2:3], s[2:3], 11
	v_cvt_pk_bf16_f32 v33, v33, v34
	v_lshl_add_u64 v[34:35], v[148:149], 0, s[2:3]
	flat_store_dwordx2 v[34:35], v[32:33]
	v_add_u32_e32 v32, -1, v41
	v_fma_f32 v33, -v32, v41, v36
	v_cmp_ge_f32_e64 s[2:3], 0, v33
	v_add_u32_e32 v33, 1, v41
	s_nop 0
	v_cndmask_b32_e64 v32, v41, v32, s[2:3]
	v_fma_f32 v41, -v33, v41, v36
	v_cmp_lt_f32_e64 s[2:3], 0, v41
	s_nop 1
	v_cndmask_b32_e64 v32, v32, v33, s[2:3]
	v_mul_f32_e32 v33, 0x37800000, v32
	v_cndmask_b32_e32 v32, v32, v33, vcc
	v_cmp_class_f32_e32 vcc, v36, v177
	s_nop 1
	v_cndmask_b32_e32 v36, v32, v36, vcc
	v_div_scale_f32 v41, s[2:3], v36, v36, 1.0
	v_rcp_f32_e32 v42, v41
	v_cvt_pk_bf16_f32 v32, v40, v37
	v_cvt_pk_bf16_f32 v33, v38, v39
	flat_store_dwordx2 v[34:35], v[32:33] offset:512
	v_fma_f32 v32, -v41, v42, 1.0
	v_fmac_f32_e32 v42, v32, v42
	v_div_scale_f32 v32, vcc, 1.0, v36, 1.0
	v_mul_f32_e32 v33, v32, v42
	v_fma_f32 v34, -v41, v33, v32
	v_fmac_f32_e32 v33, v34, v42
	v_fma_f32 v32, -v41, v33, v32
	v_div_fmas_f32 v32, v32, v42, v33
	v_div_fixup_f32 v32, v32, v36, 1.0
	v_pk_mul_f32 v[28:29], v[32:33], v[28:29] op_sel_hi:[0,1]
	v_pk_fma_f32 v[28:29], v[0:1], v[28:29], v[8:9]
	v_pk_mul_f32 v[30:31], v[32:33], v[30:31] op_sel_hi:[0,1]
	v_pk_mul_f32 v[24:25], v[32:33], v[24:25] op_sel_hi:[0,1]
	v_mul_f32_e32 v33, 0xbfb8aa3b, v28
	v_exp_f32_e32 v33, v33
	v_pk_fma_f32 v[24:25], v[4:5], v[24:25], v[12:13]
	v_mul_f32_e32 v34, 0xbfb8aa3b, v29
	v_exp_f32_e32 v34, v34
	v_pk_mul_f32 v[26:27], v[32:33], v[26:27] op_sel_hi:[0,1]
	v_add_f32_e32 v32, 1.0, v33
	v_mul_f32_e32 v33, 0xbfb8aa3b, v24
	v_exp_f32_e32 v33, v33
	v_add_f32_e32 v34, 1.0, v34
	v_mul_f32_e32 v35, 0xbfb8aa3b, v25
	v_rcp_f32_e32 v32, v32
	v_add_f32_e32 v33, 1.0, v33
	v_rcp_f32_e32 v33, v33
	v_rcp_f32_e32 v34, v34
	v_exp_f32_e32 v35, v35
	v_pk_fma_f32 v[30:31], v[2:3], v[30:31], v[10:11]
	v_pk_fma_f32 v[26:27], v[6:7], v[26:27], v[14:15]
	v_mul_f32_e32 v28, v28, v32
	v_mul_f32_e32 v32, v24, v33
	v_mul_f32_e32 v24, v29, v34
	v_add_f32_e32 v29, 1.0, v35
	v_mul_f32_e32 v33, 0xbfb8aa3b, v30
	v_mul_f32_e32 v34, 0xbfb8aa3b, v26
	v_rcp_f32_e32 v29, v29
	v_exp_f32_e32 v33, v33
	v_exp_f32_e32 v34, v34
	v_mul_f32_e32 v35, 0xbfb8aa3b, v27
	v_mul_f32_e32 v29, v25, v29
	v_add_f32_e32 v25, 1.0, v33
	v_add_f32_e32 v33, 1.0, v34
	v_mul_f32_e32 v34, 0xbfb8aa3b, v31
	v_exp_f32_e32 v34, v34
	v_exp_f32_e32 v35, v35
; __device__ __forceinline__ unsigned pk2(float lo, float hi) { return pg8::cvt_pk_bf16(lo, hi); }
; __global__ void __launch_bounds__(NWAVES * 64, 2) mk_fwd(Args args) {
;     ...
;             for (int kt = 0, tile = (G == 256) ? 64 * (vcu >> 5) + (vcu & 31) : vcu; tile < T / 64; ++kt, tile = (G == 256) ? ((kt < 2) ? 64 * (vcu >> 5) + 32 * kt + (vcu & 31) : T) : tile + G) {
;     ...
;                     for (int k = 0; k < 8; ++k) { const int tok = wave * 8 + k; const float rstd = 1.0f / sqrtf(sm[k] * (1.f / 512.f) + EPS);
;                         f32x4 x = a[k] * rstd * lg0 + lb0, y = c[k] * rstd * lg1 + lb1;
; #pragma unroll
;                         for (int e = 0; e < 4; ++e) { x[e] = x[e] * __builtin_amdgcn_rcpf(1.f + __builtin_amdgcn_exp2f(-LOG2E * x[e])); y[e] = y[e] * __builtin_amdgcn_rcpf(1.f + __builtin_amdgcn_exp2f(-LOG2E * y[e])); }
;                         bf16* orow = CAT + (size_t)(R0 + tok) * DM;
;                         *(v2u*)(orow + 4 * lane) = (v2u){pk2(x[0], x[1]), pk2(x[2], x[3])}; *(v2u*)(orow + 256 + 4 * lane) = (v2u){pk2(y[0], y[1]), pk2(y[2], y[3])}; }
;                 }
;                 __syncthreads();
	v_rcp_f32_e32 v25, v25
	v_rcp_f32_e32 v33, v33
	v_add_f32_e32 v34, 1.0, v34
	v_add_f32_e32 v35, 1.0, v35
	v_rcp_f32_e32 v34, v34
	v_rcp_f32_e32 v35, v35
	v_mul_f32_e32 v25, v30, v25
	v_mul_f32_e32 v30, v26, v33
	v_mul_f32_e32 v26, v31, v34
	v_mul_f32_e32 v31, v27, v35
	v_fmamk_f32 v27, v81, 0x3b000000, v176
	v_cvt_pk_bf16_f32 v24, v28, v24
	v_mul_f32_e32 v28, 0x4f800000, v27
	v_cmp_gt_f32_e32 vcc, s11, v27
	s_or_b32 s2, s4, 6
	s_ashr_i32 s3, s2, 31
	v_cndmask_b32_e32 v28, v27, v28, vcc
	v_sqrt_f32_e32 v33, v28
	s_lshl_b64 s[2:3], s[2:3], 11
	v_cvt_pk_bf16_f32 v25, v25, v26
	v_lshl_add_u64 v[26:27], v[148:149], 0, s[2:3]
	flat_store_dwordx2 v[26:27], v[24:25]
	v_add_u32_e32 v24, -1, v33
	v_fma_f32 v25, -v24, v33, v28
	v_cmp_ge_f32_e64 s[2:3], 0, v25
	v_add_u32_e32 v25, 1, v33
	s_nop 0
	v_cndmask_b32_e64 v24, v33, v24, s[2:3]
	v_fma_f32 v33, -v25, v33, v28
	v_cmp_lt_f32_e64 s[2:3], 0, v33
	s_nop 1
	v_cndmask_b32_e64 v24, v24, v25, s[2:3]
	v_mul_f32_e32 v25, 0x37800000, v24
	v_cndmask_b32_e32 v24, v24, v25, vcc
	v_cmp_class_f32_e32 vcc, v28, v177
	s_nop 1
	v_cndmask_b32_e32 v28, v24, v28, vcc
	v_div_scale_f32 v33, s[2:3], v28, v28, 1.0
	v_rcp_f32_e32 v34, v33
	v_cvt_pk_bf16_f32 v24, v32, v29
	v_cvt_pk_bf16_f32 v25, v30, v31
	flat_store_dwordx2 v[26:27], v[24:25] offset:512
	v_fma_f32 v24, -v33, v34, 1.0
	v_fmac_f32_e32 v34, v24, v34
	v_div_scale_f32 v24, vcc, 1.0, v28, 1.0
	v_mul_f32_e32 v25, v24, v34
	v_fma_f32 v26, -v33, v25, v24
	v_fmac_f32_e32 v25, v26, v34
	v_fma_f32 v24, -v33, v25, v24
	v_div_fmas_f32 v24, v24, v34, v25
	v_div_fixup_f32 v24, v24, v28, 1.0
	v_pk_mul_f32 v[20:21], v[24:25], v[20:21] op_sel_hi:[0,1]
	v_pk_fma_f32 v[20:21], v[0:1], v[20:21], v[8:9]
	v_pk_mul_f32 v[22:23], v[24:25], v[22:23] op_sel_hi:[0,1]
	v_pk_mul_f32 v[16:17], v[24:25], v[16:17] op_sel_hi:[0,1]
	v_mul_f32_e32 v25, 0xbfb8aa3b, v20
	v_exp_f32_e32 v25, v25
	v_pk_fma_f32 v[16:17], v[4:5], v[16:17], v[12:13]
	v_mul_f32_e32 v26, 0xbfb8aa3b, v21
	v_exp_f32_e32 v26, v26
	v_pk_mul_f32 v[18:19], v[24:25], v[18:19] op_sel_hi:[0,1]
	v_add_f32_e32 v24, 1.0, v25
	v_mul_f32_e32 v25, 0xbfb8aa3b, v16
	v_exp_f32_e32 v25, v25
	v_add_f32_e32 v26, 1.0, v26
	v_mul_f32_e32 v27, 0xbfb8aa3b, v17
	v_rcp_f32_e32 v24, v24
	v_add_f32_e32 v25, 1.0, v25
	v_rcp_f32_e32 v25, v25
	v_rcp_f32_e32 v26, v26
	v_exp_f32_e32 v27, v27
	v_pk_fma_f32 v[22:23], v[2:3], v[22:23], v[10:11]
	v_pk_fma_f32 v[18:19], v[6:7], v[18:19], v[14:15]
	v_mul_f32_e32 v20, v20, v24
	v_mul_f32_e32 v24, v16, v25
	v_mul_f32_e32 v16, v21, v26
	v_add_f32_e32 v21, 1.0, v27
	v_mul_f32_e32 v25, 0xbfb8aa3b, v22
	v_mul_f32_e32 v26, 0xbfb8aa3b, v18
	v_rcp_f32_e32 v21, v21
	v_exp_f32_e32 v25, v25
	v_exp_f32_e32 v26, v26
	v_mul_f32_e32 v27, 0xbfb8aa3b, v19
	v_mul_f32_e32 v21, v17, v21
	v_add_f32_e32 v17, 1.0, v25
	v_add_f32_e32 v25, 1.0, v26
	v_mul_f32_e32 v26, 0xbfb8aa3b, v23
	v_exp_f32_e32 v26, v26
	v_exp_f32_e32 v27, v27
	v_rcp_f32_e32 v17, v17
	v_rcp_f32_e32 v25, v25
	v_add_f32_e32 v26, 1.0, v26
	v_rcp_f32_e32 v26, v26
	v_add_f32_e32 v27, 1.0, v27
	v_rcp_f32_e32 v27, v27
	s_or_b32 s2, s4, 7
	s_ashr_i32 s3, s2, 31
	s_lshl_b64 s[2:3], s[2:3], 11
	s_add_i32 s4, s13, 1
	v_mul_f32_e32 v17, v22, v17
	v_mul_f32_e32 v22, v18, v25
	v_mul_f32_e32 v18, v23, v26
	s_cmp_eq_u32 s13, 0
	v_mul_f32_e32 v23, v19, v27
	v_cvt_pk_bf16_f32 v16, v20, v16
	v_cvt_pk_bf16_f32 v17, v17, v18
	v_lshl_add_u64 v[18:19], v[148:149], 0, s[2:3]
	s_cselect_b32 s6, s15, 0x8000
	s_and_b64 s[2:3], s[50:51], exec
	s_cselect_b32 s6, s6, s5
	s_cmpk_gt_i32 s6, 0x1ff
	s_mov_b32 s13, s4
	flat_store_dwordx2 v[18:19], v[16:17]
	v_cvt_pk_bf16_f32 v16, v24, v21
	v_cvt_pk_bf16_f32 v17, v22, v23
	flat_store_dwordx2 v[18:19], v[16:17] offset:512
	s_waitcnt lgkmcnt(0)
	s_barrier
	s_cbranch_scc1 .LBB0_361
